# v6
# speedup vs baseline: 1.0120x; 1.0022x over previous
; __device__ __forceinline__ void qkt(f32x16& p0, f32x16& p1, const char* Ks, const char* Krs, const bf16x8* qr, const char* Qrs, int r32, int hi) {
;   p0 = f32x16{}; p1 = f32x16{};
; #pragma unroll
;   for (int d0 = 0; d0 < 8; ++d0) { const int cb = (d0 * 16 + hi * 8) * 2;
;     const bf16x8 b0 = *reinterpret_cast<const bf16x8*>(Ks + KSWZ(r32, cb));
;     const bf16x8 b1 = *reinterpret_cast<const bf16x8*>(Ks + KSWZ(32 + r32, cb));
;     p0 = __builtin_amdgcn_mfma_f32_32x32x16_bf16(b0, qr[d0], p0, 0, 0, 0);
;     p1 = __builtin_amdgcn_mfma_f32_32x32x16_bf16(b1, qr[d0], p1, 0, 0, 0); }
; #pragma unroll
;   for (int d0 = 0; d0 < 4; ++d0) { const int slot = d0 * 2 + hi;
;     const bf16x8 b0 = *reinterpret_cast<const bf16x8*>(Krs + RSWZ(r32, slot));
;     const bf16x8 b1 = *reinterpret_cast<const bf16x8*>(Krs + RSWZ(32 + r32, slot));
;     const bf16x8 qf = *reinterpret_cast<const bf16x8*>(Qrs + RSWZ(r32, slot));
;     p0 = __builtin_amdgcn_mfma_f32_32x32x16_bf16(b0, qf, p0, 0, 0, 0);
;     p1 = __builtin_amdgcn_mfma_f32_32x32x16_bf16(b1, qf, p1, 0, 0, 0); }
; }
.LBB0_353:
	s_add_u32 s46, s70, 0x20000
	s_addc_u32 s47, s71, 0
	ds_read_b128 v[64:67], v169 offset:49152
	ds_read_b128 v[68:71], v169 offset:57344
	ds_read_b128 v[196:199], v170 offset:49152
	ds_read_b128 v[204:207], v170 offset:57344
	ds_read_b128 v[238:241], v171 offset:49152
	ds_read_b128 v[242:245], v171 offset:57344
	v_or_b32_e32 v164, 0x12000, v181
	v_or_b32_e32 v165, 0x13000, v181
	v_add_u32_e32 v168, v155, v181
	v_or_b32_e32 v167, 0x12000, v184
	v_add_u32_e32 v187, v155, v184
	v_exp_f32_e32 v158, v134
	v_add_f32_e32 v134, 0, v213
	s_add_u32 m0, s98, 0x8000
	s_waitcnt lgkmcnt(5)
	v_mfma_f32_32x32x16_bf16 v[80:95], v[64:67], v[124:127], 0
	global_load_lds_dwordx4 v130, s[70:71]
	v_add_f32_e32 v134, v217, v134
	v_add_f32_e32 v134, v218, v134
	v_add_f32_e32 v134, v220, v134
	v_add_f32_e32 v134, v221, v134
	v_add_f32_e32 v134, v223, v134
	v_add_f32_e32 v134, v222, v134
	v_add_f32_e32 v134, v224, v134
	s_waitcnt lgkmcnt(4)
	v_mfma_f32_32x32x16_bf16 v[64:79], v[68:71], v[124:127], 0
	v_add_f32_e32 v134, v209, v134
	v_add_f32_e32 v134, v210, v134
	v_add_f32_e32 v134, v211, v134
	v_add_f32_e32 v134, v214, v134
	v_exp_f32_e32 v146, v146
	v_add_f32_e32 v134, v212, v134
	v_exp_f32_e32 v147, v147
	s_waitcnt lgkmcnt(3)
	v_mfma_f32_32x32x16_bf16 v[80:95], v[196:199], v[120:123], v[80:95]
	v_add_f32_e32 v134, v215, v134
	v_exp_f32_e32 v144, v144
	v_add_f32_e32 v134, v216, v134
	v_exp_f32_e32 v145, v145
	v_add_f32_e32 v134, v219, v134
	v_or_b32_e32 v203, 0x13000, v184
	v_exp_f32_e32 v150, v140
	s_waitcnt lgkmcnt(2)
	v_mfma_f32_32x32x16_bf16 v[64:79], v[204:207], v[120:123], v[64:79]
	ds_read_b128 v[196:199], v172 offset:49152
	ds_read_b128 v[204:207], v172 offset:57344
	v_add_f32_e32 v134, v146, v134
	v_exp_f32_e32 v151, v141
	v_add_f32_e32 v134, v147, v134
	v_exp_f32_e32 v156, v136
	v_add_f32_e32 v134, v144, v134
	v_exp_f32_e32 v157, v137
	s_add_u32 m0, s98, 0xa000
	s_waitcnt lgkmcnt(3)
	v_mfma_f32_32x32x16_bf16 v[80:95], v[238:241], v[116:119], v[80:95]
	global_load_lds_dwordx4 v130, s[46:47]
	v_add_f32_e32 v134, v145, v134
	v_add_f32_e32 v134, v150, v134
	v_exp_f32_e32 v159, v135
	v_add_f32_e32 v134, v151, v134
	v_exp_f32_e32 v148, v148
	v_add_f32_e32 v134, v156, v134
	v_exp_f32_e32 v149, v149
	s_waitcnt lgkmcnt(2)
	v_mfma_f32_32x32x16_bf16 v[64:79], v[242:245], v[116:119], v[64:79]
	ds_read_b128 v[238:241], v173 offset:49152
	ds_read_b128 v[242:245], v173 offset:57344
	v_add_f32_e32 v134, v157, v134
	v_add_f32_e32 v134, v158, v134
	v_exp_f32_e32 v208, v143
	v_add_f32_e32 v134, v159, v134
	v_exp_f32_e32 v225, v138
	v_add_f32_e32 v134, v148, v134
	s_waitcnt lgkmcnt(3)
	v_mfma_f32_32x32x16_bf16 v[80:95], v[196:199], v[112:115], v[80:95]
	v_add_f32_e32 v134, v149, v134
	v_cvt_pk_bf16_f32 v136, v221, v223
	v_cvt_pk_bf16_f32 v135, v218, v220
	v_cvt_pk_bf16_f32 v137, v222, v224
	v_cvt_pk_bf16_f32 v138, v209, v210
	v_cvt_pk_bf16_f32 v140, v212, v215
	v_cvt_pk_bf16_f32 v141, v216, v219
	s_waitcnt lgkmcnt(2)
	v_mfma_f32_32x32x16_bf16 v[64:79], v[204:207], v[112:115], v[64:79]
	ds_read_b128 v[196:199], v174 offset:49152
	ds_read_b128 v[204:207], v174 offset:57344
	v_cvt_pk_bf16_f32 v143, v144, v145
	v_cvt_pk_bf16_f32 v144, v150, v151
	v_cvt_pk_bf16_f32 v145, v156, v157
	v_permlane32_swap_b32_e32 v135, v137
	v_permlane32_swap_b32_e32 v138, v140
	s_add_u32 m0, s98, 0x10000
	s_waitcnt lgkmcnt(3)
	v_mfma_f32_32x32x16_bf16 v[80:95], v[238:241], v[108:111], v[80:95]
	global_load_lds_dwordx4 v132, s[72:73]
	v_permlane32_swap_b32_e32 v143, v145
	s_waitcnt lgkmcnt(2)
	v_mfma_f32_32x32x16_bf16 v[64:79], v[242:245], v[108:111], v[64:79]
	ds_read_b128 v[238:241], v175 offset:49152
	ds_read_b128 v[242:245], v175 offset:57344
	s_waitcnt lgkmcnt(3)
	v_mfma_f32_32x32x16_bf16 v[80:95], v[196:199], v[104:107], v[80:95]
	s_waitcnt lgkmcnt(2)
	v_mfma_f32_32x32x16_bf16 v[64:79], v[204:207], v[104:107], v[64:79]
	ds_read_b128 v[196:199], v176 offset:49152
	ds_read_b128 v[204:207], v176 offset:57344
	s_add_u32 m0, s98, 0x4000
	s_waitcnt lgkmcnt(3)
	v_mfma_f32_32x32x16_bf16 v[80:95], v[238:241], v[100:103], v[80:95]
	global_load_lds_dwordx4 v131, s[70:71]
	s_waitcnt lgkmcnt(2)
	v_mfma_f32_32x32x16_bf16 v[64:79], v[242:245], v[100:103], v[64:79]
	ds_read_b128 v[238:241], v193
	ds_read_b128 v[242:245], v194
	ds_read_b128 v[246:249], v192
	s_waitcnt lgkmcnt(4)
	v_mfma_f32_32x32x16_bf16 v[80:95], v[196:199], v[96:99], v[80:95]
	s_waitcnt lgkmcnt(3)
	v_mfma_f32_32x32x16_bf16 v[64:79], v[204:207], v[96:99], v[64:79]
	ds_read_b128 v[196:199], v189
	ds_read_b128 v[204:207], v190
	ds_read_b128 v[226:229], v191
	s_add_u32 m0, s98, 0x6000
	s_waitcnt lgkmcnt(3)
	v_mfma_f32_32x32x16_bf16 v[80:95], v[238:241], v[246:249], v[80:95]
	global_load_lds_dwordx4 v131, s[46:47]
	s_add_u32 s70, s70, 0x40000
	s_addc_u32 s71, s71, 0
	s_add_u32 s72, s72, 0x2000
	s_addc_u32 s73, s73, 0
	s_waitcnt lgkmcnt(3)
	v_mfma_f32_32x32x16_bf16 v[64:79], v[242:245], v[246:249], v[64:79]
	ds_read_b128 v[238:241], v164
	ds_read_b128 v[242:245], v165
	ds_read_b128 v[246:249], v168
	s_waitcnt lgkmcnt(3)
	v_mfma_f32_32x32x16_bf16 v[80:95], v[196:199], v[226:229], v[80:95]
	s_waitcnt lgkmcnt(3)
	v_mfma_f32_32x32x16_bf16 v[64:79], v[204:207], v[226:229], v[64:79]
	ds_read_b128 v[196:199], v167
	ds_read_b128 v[230:233], v203
	ds_read_b128 v[234:237], v187
	s_waitcnt lgkmcnt(3)
	v_mfma_f32_32x32x16_bf16 v[80:95], v[238:241], v[246:249], v[80:95]
	v_exp_f32_e32 v207, v142
	v_cvt_pk_bf16_f32 v142, v146, v147
	v_cvt_pk_bf16_f32 v146, v158, v159
	v_cvt_pk_bf16_f32 v147, v148, v149
	v_add_f32_e32 v134, v207, v134
	s_waitcnt lgkmcnt(3)
; #define SBAR() __builtin_amdgcn_sched_barrier(0)
; __device__ __forceinline__ void partialSM(f32x16& p0, f32x16& p1, float& m_reg, float& mn, float& alpha) {
;   constexpr float C = ATT_SCALE * 1.4426950408889634f;
;   float pmax = p0[0];
; #pragma unroll
;   for (int r = 1; r < 16; ++r) pmax = fmaxf(pmax, p0[r]);
; #pragma unroll
;   for (int r = 0; r < 16; ++r) pmax = fmaxf(pmax, p1[r]);
;   { auto rr = __builtin_amdgcn_permlane32_swap(__float_as_uint(pmax), __float_as_uint(pmax), false, false);
;     pmax = fmaxf(__uint_as_float(rr[0]), __uint_as_float(rr[1])); }
;   if (__builtin_expect(__all(pmax - m_reg <= ATT_THR / ATT_SCALE), 1)) { mn = m_reg; alpha = 1.f; }
;   else { mn = fmaxf(m_reg, pmax); alpha = __builtin_amdgcn_exp2f((m_reg - mn) * C); m_reg = mn; }
;   const float mnC = -mn * C;
; #pragma unroll
;   for (int r = 0; r < 16; ++r) p0[r] = fmaf(p0[r], C, mnC);
; #pragma unroll
;   for (int r = 0; r < 16; ++r) p1[r] = fmaf(p1[r], C, mnC);
; #pragma unroll
;   for (int r = 0; r < 16; ++r) p0[r] = __builtin_amdgcn_exp2f(p0[r]);
; template <int D0> __device__ __forceinline__ void pv_one(f32x16& od, int vb, bf16x8 pa0, bf16x8 pa1, bf16x8 pa2, bf16x8 pa3) {
;   const s16x4 l0 = tr_read<v_rd_off(D0, 0, 0)>(vb), h0 = tr_read<v_rd_off(D0, 0, 1)>(vb), l1 = tr_read<v_rd_off(D0, 1, 0)>(vb), h1 = tr_read<v_rd_off(D0, 1, 1)>(vb);
;   const s16x4 l2 = tr_read<v_rd_off(D0, 2, 0)>(vb), h2 = tr_read<v_rd_off(D0, 2, 1)>(vb), l3 = tr_read<v_rd_off(D0, 3, 0)>(vb), h3 = tr_read<v_rd_off(D0, 3, 1)>(vb);
;   asm volatile("s_waitcnt lgkmcnt(0)" ::: "memory"); SBAR();
;     ...
;   od = __builtin_amdgcn_mfma_f32_32x32x16_bf16(pa0, PK(l0, h0), od, 0, 0, 0);
;   od = __builtin_amdgcn_mfma_f32_32x32x16_bf16(pa1, PK(l1, h1), od, 0, 0, 0);
;   od = __builtin_amdgcn_mfma_f32_32x32x16_bf16(pa2, PK(l2, h2), od, 0, 0, 0);
;   od = __builtin_amdgcn_mfma_f32_32x32x16_bf16(pa3, PK(l3, h3), od, 0, 0, 0);
;     ...
; }
; __device__ __forceinline__ void pv_d0(f32x16* o, int vb, bf16x8 pa0, bf16x8 pa1, bf16x8 pa2, bf16x8 pa3) {
;   pv_one<0>(o[0], vb, pa0, pa1, pa2, pa3); pv_one<1>(o[1], vb, pa0, pa1, pa2, pa3); pv_one<2>(o[2], vb, pa0, pa1, pa2, pa3); pv_one<3>(o[3], vb, pa0, pa1, pa2, pa3);
	v_mfma_f32_32x32x16_bf16 v[64:79], v[242:245], v[246:249], v[64:79]
	v_add_f32_e32 v134, v208, v134
	v_add_f32_e32 v134, v225, v134
	v_cvt_pk_bf16_f32 v148, v207, v208
	v_permlane32_swap_b32_e32 v142, v144
	s_waitcnt lgkmcnt(0)
	v_mfma_f32_32x32x16_bf16 v[80:95], v[196:199], v[234:237], v[80:95]
	v_exp_f32_e32 v226, v139
	v_cvt_pk_bf16_f32 v139, v211, v214
	s_nop 1
	v_permlane32_swap_b32_e32 v139, v141
	v_add_f32_e32 v205, v226, v134
	v_mov_b32_e32 v206, v205
	v_cvt_pk_bf16_f32 v134, v213, v217
	s_waitcnt lgkmcnt(0)
	v_mfma_f32_32x32x16_bf16 v[64:79], v[230:233], v[234:237], v[64:79]
	v_permlane32_swap_b32_e32 v205, v206
	v_permlane32_swap_b32_e32 v134, v136
	v_cvt_pk_bf16_f32 v149, v225, v226
	v_permlane32_swap_b32_e32 v146, v148
	s_nop 0
	v_permlane32_swap_b32_e32 v147, v149
	ds_read_b64_tr_b16 v[230:231], v163 offset:0
	ds_read_b64_tr_b16 v[232:233], v163 offset:0x800
	ds_read_b64_tr_b16 v[234:235], v163 offset:0x1000
	ds_read_b64_tr_b16 v[236:237], v163 offset:0x1800
	ds_read_b64_tr_b16 v[238:239], v163 offset:0x2000
	ds_read_b64_tr_b16 v[240:241], v163 offset:0x2800
	ds_read_b64_tr_b16 v[242:243], v163 offset:0x3000
	ds_read_b64_tr_b16 v[244:245], v163 offset:0x3800
	s_waitcnt lgkmcnt(0)
	s_nop 0
	v_mfma_f32_32x32x16_bf16 v[48:63], v[134:137], v[230:233], v[48:63]
	ds_read_b64_tr_b16 v[230:231], v163 offset:0x200
	ds_read_b64_tr_b16 v[232:233], v163 offset:0xa00
	v_max_f32_e32 v164, v81, v81
	v_max_f32_e32 v165, v80, v80
	v_max_f32_e32 v164, v165, v164
	v_max3_f32 v164, v164, v82, v83
	v_max3_f32 v164, v164, v84, v85
	v_mfma_f32_32x32x16_bf16 v[48:63], v[138:141], v[234:237], v[48:63]
	ds_read_b64_tr_b16 v[234:235], v163 offset:0x1200
	ds_read_b64_tr_b16 v[236:237], v163 offset:0x1a00
	v_max3_f32 v164, v164, v86, v87
	v_max3_f32 v164, v164, v88, v89
	v_max3_f32 v164, v164, v90, v91
	v_max3_f32 v164, v164, v92, v93
	v_max3_f32 v164, v164, v94, v95
	v_mfma_f32_32x32x16_bf16 v[48:63], v[142:145], v[238:241], v[48:63]
	ds_read_b64_tr_b16 v[238:239], v163 offset:0x2200
	ds_read_b64_tr_b16 v[240:241], v163 offset:0x2a00
	ds_read_b64_tr_b16 v[246:247], v163 offset:0x3200
	ds_read_b64_tr_b16 v[248:249], v163 offset:0x3a00
	v_max3_f32 v164, v164, v64, v65
	v_max3_f32 v164, v164, v66, v67
	v_max3_f32 v164, v164, v68, v69
	v_max3_f32 v164, v164, v70, v71
	v_max3_f32 v164, v164, v72, v73
	s_waitcnt lgkmcnt(0)
	v_mfma_f32_32x32x16_bf16 v[48:63], v[146:149], v[242:245], v[48:63]
	v_max3_f32 v164, v164, v74, v75
	v_max3_f32 v164, v164, v76, v77
	v_max3_f32 v164, v164, v78, v79
	v_mfma_f32_32x32x16_bf16 v[32:47], v[134:137], v[230:233], v[32:47]
	ds_read_b64_tr_b16 v[230:231], v163 offset:0x400
	ds_read_b64_tr_b16 v[232:233], v163 offset:0xc00
	v_mov_b32_e32 v165, v164
	s_nop 1
	v_permlane32_swap_b32_e32 v164, v165
	v_max_f32_e32 v165, v165, v165
	v_max_f32_e32 v164, v164, v164
	v_max_f32_e32 v164, v164, v165
	v_mfma_f32_32x32x16_bf16 v[32:47], v[138:141], v[234:237], v[32:47]
	ds_read_b64_tr_b16 v[234:235], v163 offset:0x1400
	ds_read_b64_tr_b16 v[236:237], v163 offset:0x1c00
	v_max_f32_e32 v166, v195, v195
	v_sub_f32_e32 v165, v164, v195
	v_max_f32_e32 v164, v166, v164
	v_sub_f32_e32 v166, v195, v164
	v_mul_f32_e32 v166, 0x3dd53b94, v166
	v_mfma_f32_32x32x16_bf16 v[32:47], v[142:145], v[238:241], v[32:47]
	ds_read_b64_tr_b16 v[238:239], v163 offset:0x2400
	ds_read_b64_tr_b16 v[240:241], v163 offset:0x2c00
	ds_read_b64_tr_b16 v[242:243], v163 offset:0x3400
	ds_read_b64_tr_b16 v[244:245], v163 offset:0x3c00
	v_exp_f32_e32 v166, v166
	v_cmp_ge_f32_e32 vcc, s69, v165
	s_cmp_eq_u64 vcc, exec
	s_cselect_b64 s[8:9], -1, 0
	v_cndmask_b32_e64 v208, v166, 1.0, s[8:9]
	v_cndmask_b32_e64 v167, v164, v195, s[8:9]
	v_mul_f32_e32 v207, 0xbdd53b94, v167
	s_waitcnt lgkmcnt(0)
	v_mfma_f32_32x32x16_bf16 v[32:47], v[146:149], v[246:249], v[32:47]
	v_fmamk_f32 v80, v80, 0x3dd53b94, v207
	v_fmamk_f32 v81, v81, 0x3dd53b94, v207
	v_fmamk_f32 v82, v82, 0x3dd53b94, v207
	v_fmamk_f32 v83, v83, 0x3dd53b94, v207
	v_fmamk_f32 v84, v84, 0x3dd53b94, v207
	v_fmamk_f32 v85, v85, 0x3dd53b94, v207
	v_mfma_f32_32x32x16_bf16 v[16:31], v[134:137], v[230:233], v[16:31]
	ds_read_b64_tr_b16 v[230:231], v163 offset:0x600
	ds_read_b64_tr_b16 v[232:233], v163 offset:0xe00
	v_fmamk_f32 v86, v86, 0x3dd53b94, v207
	v_fmamk_f32 v87, v87, 0x3dd53b94, v207
	v_fmamk_f32 v88, v88, 0x3dd53b94, v207
	v_fmamk_f32 v89, v89, 0x3dd53b94, v207
	v_fmamk_f32 v90, v90, 0x3dd53b94, v207
	v_fmamk_f32 v91, v91, 0x3dd53b94, v207
	v_mfma_f32_32x32x16_bf16 v[16:31], v[138:141], v[234:237], v[16:31]
	ds_read_b64_tr_b16 v[234:235], v163 offset:0x1600
	ds_read_b64_tr_b16 v[236:237], v163 offset:0x1e00
	v_fmamk_f32 v92, v92, 0x3dd53b94, v207
	v_fmamk_f32 v93, v93, 0x3dd53b94, v207
	v_fmamk_f32 v94, v94, 0x3dd53b94, v207
	v_fmamk_f32 v95, v95, 0x3dd53b94, v207
	v_fmamk_f32 v217, v64, 0x3dd53b94, v207
	v_fmamk_f32 v218, v65, 0x3dd53b94, v207
	v_mfma_f32_32x32x16_bf16 v[16:31], v[142:145], v[238:241], v[16:31]
	ds_read_b64_tr_b16 v[238:239], v163 offset:0x2600
	ds_read_b64_tr_b16 v[240:241], v163 offset:0x2e00
	ds_read_b64_tr_b16 v[246:247], v163 offset:0x3600
	ds_read_b64_tr_b16 v[248:249], v163 offset:0x3e00
	v_fmamk_f32 v219, v66, 0x3dd53b94, v207
	v_fmamk_f32 v220, v67, 0x3dd53b94, v207
	v_fmamk_f32 v221, v68, 0x3dd53b94, v207
	v_fmamk_f32 v210, v69, 0x3dd53b94, v207
	v_fmamk_f32 v211, v70, 0x3dd53b94, v207
	v_fmamk_f32 v212, v71, 0x3dd53b94, v207
	s_waitcnt lgkmcnt(0)
	v_mfma_f32_32x32x16_bf16 v[16:31], v[146:149], v[242:245], v[16:31]
	v_fmamk_f32 v213, v72, 0x3dd53b94, v207
	v_fmamk_f32 v214, v73, 0x3dd53b94, v207
	v_fmamk_f32 v215, v74, 0x3dd53b94, v207
	v_fmamk_f32 v216, v75, 0x3dd53b94, v207
	v_exp_f32_e32 v195, v85
	v_mfma_f32_32x32x16_bf16 v[0:15], v[134:137], v[230:233], v[0:15]
	v_mov_b32_e32 v134, v167
	v_fmamk_f32 v209, v76, 0x3dd53b94, v207
	v_fmamk_f32 v222, v77, 0x3dd53b94, v207
	v_fmamk_f32 v223, v78, 0x3dd53b94, v207
	v_fmac_f32_e32 v207, 0x3dd53b94, v79
	v_exp_f32_e32 v135, v88
	v_mfma_f32_32x32x16_bf16 v[0:15], v[138:141], v[234:237], v[0:15]
	v_exp_f32_e32 v136, v92
	v_exp_f32_e32 v137, v89
	v_exp_f32_e32 v138, v90
	v_exp_f32_e32 v139, v93
	v_mfma_f32_32x32x16_bf16 v[0:15], v[142:145], v[238:241], v[0:15]
	v_exp_f32_e32 v140, v94
	v_exp_f32_e32 v141, v91
	v_exp_f32_e32 v142, v95
	v_exp_f32_e32 v143, v80
	v_exp_f32_e32 v144, v81
	v_mfma_f32_32x32x16_bf16 v[0:15], v[146:149], v[246:249], v[0:15]
	v_exp_f32_e32 v145, v82
	v_exp_f32_e32 v146, v86
	v_exp_f32_e32 v147, v83
	v_exp_f32_e32 v148, v84
	v_exp_f32_e32 v149, v87
	v_cmp_gt_f32_e32 vcc, 1.0, v208
	s_cbranch_vccz .LBB0_357
; __device__ __forceinline__ void qkt(f32x16& p0, f32x16& p1, const char* Ks, const char* Krs, const bf16x8* qr, const char* Qrs, int r32, int hi) {
;   p0 = f32x16{}; p1 = f32x16{};
; #pragma unroll
;   for (int d0 = 0; d0 < 8; ++d0) { const int cb = (d0 * 16 + hi * 8) * 2;
;     const bf16x8 b0 = *reinterpret_cast<const bf16x8*>(Ks + KSWZ(r32, cb));
;     const bf16x8 b1 = *reinterpret_cast<const bf16x8*>(Ks + KSWZ(32 + r32, cb));
;     p0 = __builtin_amdgcn_mfma_f32_32x32x16_bf16(b0, qr[d0], p0, 0, 0, 0);
;     p1 = __builtin_amdgcn_mfma_f32_32x32x16_bf16(b1, qr[d0], p1, 0, 0, 0); }
; #pragma unroll
;   for (int d0 = 0; d0 < 4; ++d0) { const int slot = d0 * 2 + hi;
;     const bf16x8 b0 = *reinterpret_cast<const bf16x8*>(Krs + RSWZ(r32, slot));
;     const bf16x8 b1 = *reinterpret_cast<const bf16x8*>(Krs + RSWZ(32 + r32, slot));
;     const bf16x8 qf = *reinterpret_cast<const bf16x8*>(Qrs + RSWZ(r32, slot));
;     p0 = __builtin_amdgcn_mfma_f32_32x32x16_bf16(b0, qf, p0, 0, 0, 0);
;     p1 = __builtin_amdgcn_mfma_f32_32x32x16_bf16(b1, qf, p1, 0, 0, 0); }
; }
	s_and_saveexec_b64 s[10:11], s[6:7]
	ds_write_b32 v160, v208 offset:128
	s_or_b64 exec, exec, s[10:11]
	s_waitcnt lgkmcnt(0)
	v_add_u32_e32 v246, v253, v128
	ds_read_b128 v[230:233], v246 offset:224
	ds_read_b128 v[234:237], v246 offset:192
	ds_read_b128 v[238:241], v246 offset:160
	ds_read_b128 v[242:245], v246 offset:128
	s_waitcnt lgkmcnt(3)
	v_pk_mul_f32 v[60:61], v[60:61], v[230:231]
	s_waitcnt lgkmcnt(2)
	v_pk_mul_f32 v[56:57], v[56:57], v[234:235]
	s_waitcnt lgkmcnt(1)
	v_pk_mul_f32 v[52:53], v[52:53], v[238:239]
	v_pk_mul_f32 v[62:63], v[62:63], v[232:233]
	v_pk_mul_f32 v[58:59], v[58:59], v[236:237]
	v_pk_mul_f32 v[54:55], v[54:55], v[240:241]
	s_waitcnt lgkmcnt(0)
	v_pk_mul_f32 v[50:51], v[50:51], v[244:245]
	v_pk_mul_f32 v[48:49], v[48:49], v[242:243]
	v_pk_mul_f32 v[44:45], v[44:45], v[230:231]
	v_pk_mul_f32 v[40:41], v[40:41], v[234:235]
	v_pk_mul_f32 v[36:37], v[36:37], v[238:239]
	v_pk_mul_f32 v[46:47], v[46:47], v[232:233]
	v_pk_mul_f32 v[42:43], v[42:43], v[236:237]
	v_pk_mul_f32 v[38:39], v[38:39], v[240:241]
	v_pk_mul_f32 v[34:35], v[34:35], v[244:245]
	v_pk_mul_f32 v[32:33], v[32:33], v[242:243]
	v_pk_mul_f32 v[28:29], v[28:29], v[230:231]
	v_pk_mul_f32 v[24:25], v[24:25], v[234:235]
	v_pk_mul_f32 v[20:21], v[20:21], v[238:239]
	v_pk_mul_f32 v[30:31], v[30:31], v[232:233]
	v_pk_mul_f32 v[26:27], v[26:27], v[236:237]
	v_pk_mul_f32 v[22:23], v[22:23], v[240:241]
	v_pk_mul_f32 v[18:19], v[18:19], v[244:245]
	v_pk_mul_f32 v[16:17], v[16:17], v[242:243]
	v_pk_mul_f32 v[12:13], v[12:13], v[230:231]
	v_pk_mul_f32 v[8:9], v[8:9], v[234:235]
	v_pk_mul_f32 v[4:5], v[4:5], v[238:239]
	v_pk_mul_f32 v[14:15], v[14:15], v[232:233]
	v_pk_mul_f32 v[10:11], v[10:11], v[236:237]
	v_pk_mul_f32 v[6:7], v[6:7], v[240:241]
	v_pk_mul_f32 v[2:3], v[2:3], v[244:245]
	v_pk_mul_f32 v[0:1], v[0:1], v[242:243]
.LBB0_357:
	s_waitcnt vmcnt(0)
	s_waitcnt lgkmcnt(0)
	s_barrier
	s_add_u32 s46, s70, 0x20000
	s_addc_u32 s47, s71, 0
	ds_read_b128 v[64:67], v169 offset:32768
	ds_read_b128 v[68:71], v169 offset:40960
	ds_read_b128 v[224:227], v170 offset:32768
	ds_read_b128 v[228:231], v170 offset:40960
	ds_read_b128 v[240:243], v171 offset:32768
	ds_read_b128 v[244:247], v171 offset:40960
	v_exp_f32_e32 v159, v210
	v_add_f32_e32 v210, 0, v143
	s_add_u32 m0, s98, 0xc000
	s_waitcnt lgkmcnt(5)
	v_mfma_f32_32x32x16_bf16 v[80:95], v[64:67], v[124:127], 0
	global_load_lds_dwordx4 v130, s[70:71]
	v_add_f32_e32 v210, v144, v210
	v_add_f32_e32 v210, v145, v210
	v_add_f32_e32 v210, v147, v210
	v_add_f32_e32 v210, v148, v210
	v_add_f32_e32 v210, v195, v210
	v_add_f32_e32 v210, v146, v210
	v_add_f32_e32 v210, v149, v210
	s_waitcnt lgkmcnt(4)
	v_mfma_f32_32x32x16_bf16 v[64:79], v[68:71], v[124:127], 0
	v_add_f32_e32 v210, v135, v210
	v_add_f32_e32 v210, v137, v210
	v_add_f32_e32 v210, v138, v210
	v_add_f32_e32 v210, v141, v210
	v_exp_f32_e32 v150, v217
	v_add_f32_e32 v210, v136, v210
	v_exp_f32_e32 v151, v218
	s_waitcnt lgkmcnt(3)
	v_mfma_f32_32x32x16_bf16 v[80:95], v[224:227], v[120:123], v[80:95]
	v_add_f32_e32 v210, v139, v210
	v_exp_f32_e32 v156, v219
	v_add_f32_e32 v210, v140, v210
	v_exp_f32_e32 v157, v220
	v_add_f32_e32 v210, v142, v210
	v_exp_f32_e32 v158, v221
	v_add_f32_e32 v210, v150, v210
	s_waitcnt lgkmcnt(2)
	v_mfma_f32_32x32x16_bf16 v[64:79], v[228:231], v[120:123], v[64:79]
	ds_read_b128 v[224:227], v172 offset:32768
	ds_read_b128 v[228:231], v172 offset:40960
	v_add_f32_e32 v210, v151, v210
	v_exp_f32_e32 v217, v211
	v_add_f32_e32 v210, v156, v210
	v_exp_f32_e32 v218, v212
	v_add_f32_e32 v210, v157, v210
	v_exp_f32_e32 v219, v213
	s_add_u32 m0, s98, 0xe000
	s_waitcnt lgkmcnt(3)
	v_mfma_f32_32x32x16_bf16 v[80:95], v[240:243], v[116:119], v[80:95]
	global_load_lds_dwordx4 v130, s[46:47]
	v_add_f32_e32 v210, v158, v210
	v_exp_f32_e32 v214, v214
	v_add_f32_e32 v210, v159, v210
	v_exp_f32_e32 v215, v215
	v_add_f32_e32 v210, v217, v210
	v_exp_f32_e32 v216, v216
	v_add_f32_e32 v210, v218, v210
	s_waitcnt lgkmcnt(2)
	v_mfma_f32_32x32x16_bf16 v[64:79], v[244:247], v[116:119], v[64:79]
	ds_read_b128 v[240:243], v173 offset:32768
	ds_read_b128 v[244:247], v173 offset:40960
	v_exp_f32_e32 v209, v209
	v_add_f32_e32 v210, v219, v210
	v_exp_f32_e32 v220, v222
	v_add_f32_e32 v210, v214, v210
	v_exp_f32_e32 v221, v223
	v_add_f32_e32 v210, v215, v210
	s_waitcnt lgkmcnt(3)
	v_mfma_f32_32x32x16_bf16 v[80:95], v[224:227], v[112:115], v[80:95]
	v_exp_f32_e32 v207, v207
	v_add_f32_e32 v210, v216, v210
	v_add_f32_e32 v210, v209, v210
	v_add_f32_e32 v210, v220, v210
	v_add_f32_e32 v210, v221, v210
	v_cvt_pk_bf16_f32 v211, v145, v147
	v_cvt_pk_bf16_f32 v212, v148, v195
	s_waitcnt lgkmcnt(2)
	v_mfma_f32_32x32x16_bf16 v[64:79], v[228:231], v[112:115], v[64:79]
	ds_read_b128 v[224:227], v174 offset:32768
	ds_read_b128 v[228:231], v174 offset:40960
	v_cvt_pk_bf16_f32 v213, v146, v149
	v_cvt_pk_bf16_f32 v145, v138, v141
	v_cvt_pk_bf16_f32 v146, v136, v139
	v_cvt_pk_bf16_f32 v147, v140, v142
	v_cvt_pk_bf16_f32 v136, v150, v151
	v_cvt_pk_bf16_f32 v138, v158, v159
	s_add_u32 m0, s98, 0x12000
	s_waitcnt lgkmcnt(3)
	v_mfma_f32_32x32x16_bf16 v[80:95], v[240:243], v[108:111], v[80:95]
	global_load_lds_dwordx4 v132, s[72:73]
	v_cvt_pk_bf16_f32 v139, v217, v218
	v_cvt_pk_bf16_f32 v140, v219, v214
	v_cvt_pk_bf16_f32 v141, v215, v216
	v_cvt_pk_bf16_f32 v142, v209, v220
	v_permlane32_swap_b32_e32 v211, v213
	v_permlane32_swap_b32_e32 v145, v147
	s_waitcnt lgkmcnt(2)
	v_mfma_f32_32x32x16_bf16 v[64:79], v[244:247], v[108:111], v[64:79]
	ds_read_b128 v[240:243], v175 offset:32768
	ds_read_b128 v[244:247], v175 offset:40960
	v_permlane32_swap_b32_e32 v136, v138
	v_permlane32_swap_b32_e32 v140, v142
	s_waitcnt lgkmcnt(3)
; __device__ __forceinline__ void qkt(f32x16& p0, f32x16& p1, const char* Ks, const char* Krs, const bf16x8* qr, const char* Qrs, int r32, int hi) {
;   p0 = f32x16{}; p1 = f32x16{};
; #pragma unroll
;   for (int d0 = 0; d0 < 8; ++d0) { const int cb = (d0 * 16 + hi * 8) * 2;
;     const bf16x8 b0 = *reinterpret_cast<const bf16x8*>(Ks + KSWZ(r32, cb));
;     const bf16x8 b1 = *reinterpret_cast<const bf16x8*>(Ks + KSWZ(32 + r32, cb));
;     p0 = __builtin_amdgcn_mfma_f32_32x32x16_bf16(b0, qr[d0], p0, 0, 0, 0);
;     p1 = __builtin_amdgcn_mfma_f32_32x32x16_bf16(b1, qr[d0], p1, 0, 0, 0); }
; #pragma unroll
;   for (int d0 = 0; d0 < 4; ++d0) { const int slot = d0 * 2 + hi;
;     const bf16x8 b0 = *reinterpret_cast<const bf16x8*>(Krs + RSWZ(r32, slot));
;     const bf16x8 b1 = *reinterpret_cast<const bf16x8*>(Krs + RSWZ(32 + r32, slot));
;     const bf16x8 qf = *reinterpret_cast<const bf16x8*>(Qrs + RSWZ(r32, slot));
;     p0 = __builtin_amdgcn_mfma_f32_32x32x16_bf16(b0, qf, p0, 0, 0, 0);
;     p1 = __builtin_amdgcn_mfma_f32_32x32x16_bf16(b1, qf, p1, 0, 0, 0); }
; }
; __device__ __forceinline__ int v_st(int k, int c) { const int kk = (k & ~0xC) | ((k & 4) << 1) | ((k & 8) >> 1); return ((kk >> 3) * 4 + (c >> 5)) * 512 + ((kk & 7) * 32 + (c & 31)) * 2; }
; __device__ __forceinline__ int v_rd_base(int lane) { return ((lane & 3) << 3) | (((lane >> 2) & 3) << 6) | (((lane >> 4) & 1) << 5) | (((lane >> 5) & 1) << 8); }
; template <int OFF> __device__ __forceinline__ s16x4 tr_read(int vb) {
;   s16x4 r; asm volatile("ds_read_b64_tr_b16 %0, %1 offset:%2" : "=&v"(r) : "v"(vb), "i"(OFF) : "memory"); return r;
; }
; template <int D0> __device__ __forceinline__ void pv_one(f32x16& od, int vb, bf16x8 pa0, bf16x8 pa1, bf16x8 pa2, bf16x8 pa3) {
;   const s16x4 l0 = tr_read<v_rd_off(D0, 0, 0)>(vb), h0 = tr_read<v_rd_off(D0, 0, 1)>(vb), l1 = tr_read<v_rd_off(D0, 1, 0)>(vb), h1 = tr_read<v_rd_off(D0, 1, 1)>(vb);
;   const s16x4 l2 = tr_read<v_rd_off(D0, 2, 0)>(vb), h2 = tr_read<v_rd_off(D0, 2, 1)>(vb), l3 = tr_read<v_rd_off(D0, 3, 0)>(vb), h3 = tr_read<v_rd_off(D0, 3, 1)>(vb);
;   asm volatile("s_waitcnt lgkmcnt(0)" ::: "memory"); SBAR();
;     ...
;   od = __builtin_amdgcn_mfma_f32_32x32x16_bf16(pa0, PK(l0, h0), od, 0, 0, 0);
;   od = __builtin_amdgcn_mfma_f32_32x32x16_bf16(pa1, PK(l1, h1), od, 0, 0, 0);
;   od = __builtin_amdgcn_mfma_f32_32x32x16_bf16(pa2, PK(l2, h2), od, 0, 0, 0);
	v_mfma_f32_32x32x16_bf16 v[80:95], v[224:227], v[104:107], v[80:95]
	s_waitcnt lgkmcnt(2)
	v_mfma_f32_32x32x16_bf16 v[64:79], v[228:231], v[104:107], v[64:79]
	ds_read_b128 v[224:227], v176 offset:32768
	ds_read_b128 v[228:231], v176 offset:40960
	s_mov_b32 m0, s98
	s_waitcnt lgkmcnt(3)
	v_mfma_f32_32x32x16_bf16 v[80:95], v[240:243], v[100:103], v[80:95]
	global_load_lds_dwordx4 v131, s[70:71]
	s_waitcnt lgkmcnt(2)
	v_mfma_f32_32x32x16_bf16 v[64:79], v[244:247], v[100:103], v[64:79]
	ds_read_b128 v[240:243], v177
	ds_read_b128 v[244:247], v178
	ds_read_b128 v[248:251], v192
	s_waitcnt lgkmcnt(4)
	v_mfma_f32_32x32x16_bf16 v[80:95], v[224:227], v[96:99], v[80:95]
	s_waitcnt lgkmcnt(3)
	v_mfma_f32_32x32x16_bf16 v[64:79], v[228:231], v[96:99], v[64:79]
	ds_read_b128 v[224:227], v179
	ds_read_b128 v[228:231], v180
	ds_read_b128 v[232:235], v191
	s_add_u32 m0, s98, 0x2000
	s_waitcnt lgkmcnt(3)
	v_mfma_f32_32x32x16_bf16 v[80:95], v[240:243], v[248:251], v[80:95]
	global_load_lds_dwordx4 v131, s[46:47]
	s_add_u32 s70, s70, 0x40000
	s_addc_u32 s71, s71, 0
	s_add_u32 s72, s72, 0x2000
	s_addc_u32 s73, s73, 0
	s_waitcnt lgkmcnt(3)
	v_mfma_f32_32x32x16_bf16 v[64:79], v[244:247], v[248:251], v[64:79]
	ds_read_b128 v[240:243], v182
	ds_read_b128 v[244:247], v183
	ds_read_b128 v[248:251], v168
	s_waitcnt lgkmcnt(3)
	v_mfma_f32_32x32x16_bf16 v[80:95], v[224:227], v[232:235], v[80:95]
	s_waitcnt lgkmcnt(3)
	v_mfma_f32_32x32x16_bf16 v[64:79], v[228:231], v[232:235], v[64:79]
	ds_read_b128 v[224:227], v185
	ds_read_b128 v[228:231], v186
	ds_read_b128 v[232:235], v187
	s_waitcnt lgkmcnt(3)
	v_mfma_f32_32x32x16_bf16 v[80:95], v[240:243], v[248:251], v[80:95]
	s_waitcnt lgkmcnt(3)
	v_mfma_f32_32x32x16_bf16 v[64:79], v[244:247], v[248:251], v[64:79]
	s_waitcnt lgkmcnt(0)
	v_mfma_f32_32x32x16_bf16 v[80:95], v[224:227], v[232:235], v[80:95]
	v_add_f32_e32 v225, v207, v210
	v_mov_b32_e32 v226, v225
	s_nop 1
	v_permlane32_swap_b32_e32 v225, v226
	v_cvt_pk_bf16_f32 v210, v143, v144
	v_cvt_pk_bf16_f32 v144, v135, v137
	v_cvt_pk_bf16_f32 v137, v156, v157
	s_waitcnt lgkmcnt(0)
	v_mfma_f32_32x32x16_bf16 v[64:79], v[228:231], v[232:235], v[64:79]
	v_cvt_pk_bf16_f32 v143, v221, v207
	v_permlane32_swap_b32_e32 v210, v212
	v_permlane32_swap_b32_e32 v144, v146
	v_permlane32_swap_b32_e32 v137, v139
	v_permlane32_swap_b32_e32 v141, v143
	ds_read_b64_tr_b16 v[240:241], v162 offset:0
	ds_read_b64_tr_b16 v[242:243], v162 offset:0x800
	ds_read_b64_tr_b16 v[244:245], v162 offset:0x1000
	ds_read_b64_tr_b16 v[246:247], v162 offset:0x1800
	ds_read_b64_tr_b16 v[248:249], v162 offset:0x2000
	ds_read_b64_tr_b16 v[250:251], v162 offset:0x2800
	ds_read_b64_tr_b16 v[148:149], v162 offset:0x3000
	ds_read_b64_tr_b16 v[150:151], v162 offset:0x3800
	s_waitcnt lgkmcnt(0)
	s_nop 0
	v_mfma_f32_32x32x16_bf16 v[48:63], v[210:213], v[240:243], v[48:63]
	ds_read_b64_tr_b16 v[240:241], v162 offset:0x200
	ds_read_b64_tr_b16 v[242:243], v162 offset:0xa00
	v_max_f32_e32 v164, v81, v81
	v_max_f32_e32 v165, v80, v80
	v_max_f32_e32 v164, v165, v164
	v_max3_f32 v164, v164, v82, v83
	v_max3_f32 v164, v164, v84, v85
	v_mfma_f32_32x32x16_bf16 v[48:63], v[144:147], v[244:247], v[48:63]
	ds_read_b64_tr_b16 v[244:245], v162 offset:0x1200
	ds_read_b64_tr_b16 v[246:247], v162 offset:0x1a00
	v_max3_f32 v164, v164, v86, v87
	v_max3_f32 v164, v164, v88, v89
	v_max3_f32 v164, v164, v90, v91
	v_max3_f32 v164, v164, v92, v93
	v_max3_f32 v164, v164, v94, v95
	v_mfma_f32_32x32x16_bf16 v[48:63], v[136:139], v[248:251], v[48:63]
	ds_read_b64_tr_b16 v[248:249], v162 offset:0x2200
	ds_read_b64_tr_b16 v[250:251], v162 offset:0x2a00
	ds_read_b64_tr_b16 v[156:157], v162 offset:0x3200
	ds_read_b64_tr_b16 v[158:159], v162 offset:0x3a00
	v_max3_f32 v164, v164, v64, v65
	v_max3_f32 v164, v164, v66, v67
	v_max3_f32 v164, v164, v68, v69
	v_max3_f32 v164, v164, v70, v71
	v_max3_f32 v164, v164, v72, v73
	s_waitcnt lgkmcnt(0)
	v_mfma_f32_32x32x16_bf16 v[48:63], v[140:143], v[148:151], v[48:63]
	v_max3_f32 v164, v164, v74, v75
	v_max3_f32 v164, v164, v76, v77
	v_max3_f32 v164, v164, v78, v79
	v_mfma_f32_32x32x16_bf16 v[32:47], v[210:213], v[240:243], v[32:47]
	ds_read_b64_tr_b16 v[148:149], v162 offset:0x400
	ds_read_b64_tr_b16 v[150:151], v162 offset:0xc00
	ds_read_b64_tr_b16 v[240:241], v162 offset:0x1400
	ds_read_b64_tr_b16 v[242:243], v162 offset:0x1c00
	v_mov_b32_e32 v165, v164
	s_nop 1
	v_permlane32_swap_b32_e32 v164, v165
	v_max_f32_e32 v165, v165, v165
	v_max_f32_e32 v164, v164, v164
	v_max_f32_e32 v164, v164, v165
	v_mfma_f32_32x32x16_bf16 v[32:47], v[144:147], v[244:247], v[32:47]
	ds_read_b64_tr_b16 v[244:245], v162 offset:0x2400
	ds_read_b64_tr_b16 v[246:247], v162 offset:0x2c00
	v_max_f32_e32 v166, v134, v134
	v_sub_f32_e32 v165, v164, v134
	v_max_f32_e32 v164, v166, v164
	v_sub_f32_e32 v166, v134, v164
	v_mul_f32_e32 v166, 0x3dd53b94, v166
	v_mfma_f32_32x32x16_bf16 v[32:47], v[136:139], v[248:251], v[32:47]
	ds_read_b64_tr_b16 v[248:249], v162 offset:0x3400
	ds_read_b64_tr_b16 v[250:251], v162 offset:0x3c00
	v_exp_f32_e32 v166, v166
	v_cmp_ge_f32_e32 vcc, s69, v165
	s_cmp_eq_u64 vcc, exec
	s_cselect_b64 s[8:9], -1, 0
	v_cndmask_b32_e64 v207, v166, 1.0, s[8:9]
	v_cndmask_b32_e64 v195, v164, v134, s[8:9]
	v_mul_f32_e32 v168, 0xbdd53b94, v195
	v_mov_b32_e32 v187, v168
	s_waitcnt lgkmcnt(0)
; __device__ __forceinline__ void partialSM(f32x16& p0, f32x16& p1, float& m_reg, float& mn, float& alpha) {
;   constexpr float C = ATT_SCALE * 1.4426950408889634f;
;   float pmax = p0[0];
; #pragma unroll
;   for (int r = 1; r < 16; ++r) pmax = fmaxf(pmax, p0[r]);
; #pragma unroll
;   for (int r = 0; r < 16; ++r) pmax = fmaxf(pmax, p1[r]);
;   { auto rr = __builtin_amdgcn_permlane32_swap(__float_as_uint(pmax), __float_as_uint(pmax), false, false);
;     pmax = fmaxf(__uint_as_float(rr[0]), __uint_as_float(rr[1])); }
;   if (__builtin_expect(__all(pmax - m_reg <= ATT_THR / ATT_SCALE), 1)) { mn = m_reg; alpha = 1.f; }
;   else { mn = fmaxf(m_reg, pmax); alpha = __builtin_amdgcn_exp2f((m_reg - mn) * C); m_reg = mn; }
;   const float mnC = -mn * C;
; #pragma unroll
;   for (int r = 0; r < 16; ++r) p0[r] = fmaf(p0[r], C, mnC);
; #pragma unroll
;   for (int r = 0; r < 16; ++r) p1[r] = fmaf(p1[r], C, mnC);
; #pragma unroll
;   for (int r = 0; r < 16; ++r) p0[r] = __builtin_amdgcn_exp2f(p0[r]);
	v_mfma_f32_32x32x16_bf16 v[32:47], v[140:143], v[156:159], v[32:47]
	v_fmamk_f32 v80, v80, 0x3dd53b94, v168
	v_fmamk_f32 v81, v81, 0x3dd53b94, v168
	v_fmamk_f32 v82, v82, 0x3dd53b94, v168
	v_fmamk_f32 v83, v83, 0x3dd53b94, v168
	v_fmamk_f32 v84, v84, 0x3dd53b94, v168
	v_fmamk_f32 v85, v85, 0x3dd53b94, v168
	v_mfma_f32_32x32x16_bf16 v[16:31], v[210:213], v[148:151], v[16:31]
	ds_read_b64_tr_b16 v[148:149], v162 offset:0x600
	ds_read_b64_tr_b16 v[150:151], v162 offset:0xe00
	ds_read_b64_tr_b16 v[156:157], v162 offset:0x1600
	ds_read_b64_tr_b16 v[158:159], v162 offset:0x1e00
	v_fmamk_f32 v86, v86, 0x3dd53b94, v168
	v_fmamk_f32 v87, v87, 0x3dd53b94, v168
	v_fmamk_f32 v88, v88, 0x3dd53b94, v168
	v_fmamk_f32 v89, v89, 0x3dd53b94, v168
	v_fmamk_f32 v90, v90, 0x3dd53b94, v168
	v_fmamk_f32 v91, v91, 0x3dd53b94, v168
	v_mfma_f32_32x32x16_bf16 v[16:31], v[144:147], v[240:243], v[16:31]
	ds_read_b64_tr_b16 v[240:241], v162 offset:0x2600
	ds_read_b64_tr_b16 v[242:243], v162 offset:0x2e00
	v_fmamk_f32 v92, v92, 0x3dd53b94, v168
	v_fmamk_f32 v93, v93, 0x3dd53b94, v168
	v_fmamk_f32 v94, v94, 0x3dd53b94, v168
	v_fmac_f32_e32 v187, 0x3dd53b94, v95
	v_fmamk_f32 v134, v72, 0x3dd53b94, v168
	v_fmamk_f32 v135, v73, 0x3dd53b94, v168
	v_mfma_f32_32x32x16_bf16 v[16:31], v[136:139], v[244:247], v[16:31]
	ds_read_b64_tr_b16 v[244:245], v162 offset:0x3600
	ds_read_b64_tr_b16 v[246:247], v162 offset:0x3e00
	v_exp_f32_e32 v217, v81
	v_exp_f32_e32 v218, v82
	v_exp_f32_e32 v220, v83
	v_exp_f32_e32 v221, v84
	s_waitcnt lgkmcnt(0)
	v_mfma_f32_32x32x16_bf16 v[16:31], v[140:143], v[248:251], v[16:31]
	v_exp_f32_e32 v223, v85
	v_exp_f32_e32 v222, v86
	v_exp_f32_e32 v224, v87
	v_exp_f32_e32 v209, v88
	v_mfma_f32_32x32x16_bf16 v[0:15], v[210:213], v[148:151], v[0:15]
	v_fmamk_f32 v148, v74, 0x3dd53b94, v168
	v_fmamk_f32 v149, v75, 0x3dd53b94, v168
	v_exp_f32_e32 v214, v91
	v_exp_f32_e32 v215, v93
	v_exp_f32_e32 v216, v94
	v_mfma_f32_32x32x16_bf16 v[0:15], v[144:147], v[156:159], v[0:15]
	v_fmamk_f32 v146, v64, 0x3dd53b94, v168
	v_fmamk_f32 v147, v65, 0x3dd53b94, v168
	v_fmamk_f32 v144, v66, 0x3dd53b94, v168
	v_fmamk_f32 v145, v67, 0x3dd53b94, v168
	v_exp_f32_e32 v219, v187
	v_exp_f32_e32 v213, v80
	v_mfma_f32_32x32x16_bf16 v[0:15], v[136:139], v[240:243], v[0:15]
	v_fmamk_f32 v136, v70, 0x3dd53b94, v168
	v_fmamk_f32 v137, v71, 0x3dd53b94, v168
	v_fmamk_f32 v138, v78, 0x3dd53b94, v168
	v_fmamk_f32 v139, v79, 0x3dd53b94, v168
	v_exp_f32_e32 v210, v89
	v_exp_f32_e32 v211, v90
	v_mfma_f32_32x32x16_bf16 v[0:15], v[140:143], v[244:247], v[0:15]
	v_fmamk_f32 v140, v68, 0x3dd53b94, v168
	v_fmamk_f32 v141, v69, 0x3dd53b94, v168
	v_fmamk_f32 v142, v76, 0x3dd53b94, v168
	v_fmamk_f32 v143, v77, 0x3dd53b94, v168
	v_exp_f32_e32 v212, v92
	v_cmp_gt_f32_e32 vcc, 1.0, v207
	s_cbranch_vccz .LBB0_361
	s_and_saveexec_b64 s[10:11], s[6:7]
	ds_write_b32 v160, v207 offset:128
	s_or_b64 exec, exec, s[10:11]
	s_waitcnt lgkmcnt(0)
	v_add_u32_e32 v150, v253, v128
	ds_read_b128 v[240:243], v150 offset:224
	ds_read_b128 v[244:247], v150 offset:192
	ds_read_b128 v[248:251], v150 offset:160
	ds_read_b128 v[156:159], v150 offset:128
	s_waitcnt lgkmcnt(3)
	v_pk_mul_f32 v[60:61], v[60:61], v[240:241]
	s_waitcnt lgkmcnt(2)
	v_pk_mul_f32 v[56:57], v[56:57], v[244:245]
	s_waitcnt lgkmcnt(1)
	v_pk_mul_f32 v[52:53], v[52:53], v[248:249]
	v_pk_mul_f32 v[62:63], v[62:63], v[242:243]
	v_pk_mul_f32 v[58:59], v[58:59], v[246:247]
	v_pk_mul_f32 v[54:55], v[54:55], v[250:251]
	s_waitcnt lgkmcnt(0)
	v_pk_mul_f32 v[50:51], v[50:51], v[158:159]
	v_pk_mul_f32 v[48:49], v[48:49], v[156:157]
	v_pk_mul_f32 v[44:45], v[44:45], v[240:241]
	v_pk_mul_f32 v[40:41], v[40:41], v[244:245]
	v_pk_mul_f32 v[36:37], v[36:37], v[248:249]
	v_pk_mul_f32 v[46:47], v[46:47], v[242:243]
	v_pk_mul_f32 v[42:43], v[42:43], v[246:247]
	v_pk_mul_f32 v[38:39], v[38:39], v[250:251]
	v_pk_mul_f32 v[34:35], v[34:35], v[158:159]
	v_pk_mul_f32 v[32:33], v[32:33], v[156:157]
	v_pk_mul_f32 v[28:29], v[28:29], v[240:241]
	v_pk_mul_f32 v[24:25], v[24:25], v[244:245]
	v_pk_mul_f32 v[20:21], v[20:21], v[248:249]
	v_pk_mul_f32 v[30:31], v[30:31], v[242:243]
	v_pk_mul_f32 v[26:27], v[26:27], v[246:247]
	v_pk_mul_f32 v[22:23], v[22:23], v[250:251]
	v_pk_mul_f32 v[18:19], v[18:19], v[158:159]
	v_pk_mul_f32 v[16:17], v[16:17], v[156:157]
	v_pk_mul_f32 v[12:13], v[12:13], v[240:241]
	v_pk_mul_f32 v[8:9], v[8:9], v[244:245]
	v_pk_mul_f32 v[4:5], v[4:5], v[248:249]
	v_pk_mul_f32 v[14:15], v[14:15], v[242:243]
	v_pk_mul_f32 v[10:11], v[10:11], v[246:247]
	v_pk_mul_f32 v[6:7], v[6:7], v[250:251]
	v_pk_mul_f32 v[2:3], v[2:3], v[158:159]
	v_pk_mul_f32 v[0:1], v[0:1], v[156:157]
